# w_ffn2_out transposes in the phase-1 tail queue; GLA loop at its better placement; unreachable padding totals 4096 bytes so all later code keeps its address modulo 4 KiB
# speedup vs baseline: 1.0054x; 1.0054x over previous
; #define BAR_LDS() do { asm volatile("s_waitcnt lgkmcnt(0)" ::: "memory"); __builtin_amdgcn_s_barrier(); asm volatile("" ::: "memory"); } while (0)
; __device__ __forceinline__ void gla_item(const Params& p, unsigned char* sm, int h, int job0, int jobstride, int nchunks, int tok0, int nvalid, const float* s_init, float* s_out, const int TIDX) {
;     ...
;         if (ci + 1 < nchunks) { GLA_STORE(); }
;         BAR_LDS();
;     }
.LBB0_173:
	s_or_b64 exec, exec, vcc
	s_branch .Lgla_next
	s_nop 0
	s_nop 0
	s_nop 0
	s_nop 0
	s_nop 0
	s_nop 0
	s_nop 0
	s_nop 0
	s_nop 0
	s_nop 0
	s_nop 0
	s_nop 0
	s_nop 0
	s_nop 0
	s_nop 0
	s_nop 0
	s_nop 0
	s_nop 0
	s_nop 0
	s_nop 0
	s_nop 0
	s_nop 0
	s_nop 0
	s_nop 0
	s_nop 0
	s_nop 0
	s_nop 0
	s_nop 0
	s_nop 0
	s_nop 0
	s_nop 0
	s_nop 0
	s_nop 0
	s_nop 0
	s_nop 0
	s_nop 0
	s_nop 0
	s_nop 0
	s_nop 0
	s_nop 0
	s_nop 0
	s_nop 0
	s_nop 0
	s_nop 0
	s_nop 0
	s_nop 0
	s_nop 0
	s_nop 0
	s_nop 0
	s_nop 0
	s_nop 0
	s_nop 0
	s_nop 0
	s_nop 0
	s_nop 0
	s_nop 0
	s_nop 0
	s_nop 0
	s_nop 0
	s_nop 0
	s_nop 0
	s_nop 0
	s_nop 0
	s_nop 0
	s_nop 0
	s_nop 0
	s_nop 0
	s_nop 0
	s_nop 0
	s_nop 0
	s_nop 0
	s_nop 0
	s_nop 0
	s_nop 0
	s_nop 0
	s_nop 0
	s_nop 0
	s_nop 0
	s_nop 0
	s_nop 0
	s_nop 0
	s_nop 0
	s_nop 0
	s_nop 0
	s_nop 0
	s_nop 0
	s_nop 0
	s_nop 0
	s_nop 0
	s_nop 0
	s_nop 0
	s_nop 0
	s_nop 0
	s_nop 0
	s_nop 0
	s_nop 0
	s_nop 0
	s_nop 0
	s_nop 0
	s_nop 0
	s_nop 0
	s_nop 0
	s_nop 0
	s_nop 0
	s_nop 0
	s_nop 0
	s_nop 0
	s_nop 0
	s_nop 0
	s_nop 0
	s_nop 0
	s_nop 0
	s_nop 0
	s_nop 0
	s_nop 0
	s_nop 0
	s_nop 0
	s_nop 0
	s_nop 0
	s_nop 0
	s_nop 0
	s_nop 0
	s_nop 0
	s_nop 0
	s_nop 0
	s_nop 0
	s_nop 0
	s_nop 0
	s_nop 0
	s_nop 0
	s_nop 0
	s_nop 0
	s_nop 0
	s_nop 0
	s_nop 0
	s_nop 0
	s_nop 0
	s_nop 0
	s_nop 0
	s_nop 0
	s_nop 0
	s_nop 0
	s_nop 0
	s_nop 0
	s_nop 0
	s_nop 0
	s_nop 0
	s_nop 0
	s_nop 0
	s_nop 0
	s_nop 0
	s_nop 0
	s_nop 0
	s_nop 0
	s_nop 0
	s_nop 0
	s_nop 0
	s_nop 0
	s_nop 0
	s_nop 0
	s_nop 0
	s_nop 0
	s_nop 0
	s_nop 0
	s_nop 0
	s_nop 0
	s_nop 0
	s_nop 0
	s_nop 0
	s_nop 0
	s_nop 0
	s_nop 0
	s_nop 0
	s_nop 0
	s_nop 0
	s_nop 0
	s_nop 0
	s_nop 0
	s_nop 0
	s_nop 0
	s_nop 0
	s_nop 0
	s_nop 0
	s_nop 0
	s_nop 0
	s_nop 0
	s_nop 0
	s_nop 0
	s_nop 0
	s_nop 0
	s_nop 0
	s_nop 0
	s_nop 0
	s_nop 0
	s_nop 0
	s_nop 0
	s_nop 0
	s_nop 0
	s_nop 0
	s_nop 0
	s_nop 0
	s_nop 0
	s_nop 0
	s_nop 0
	s_nop 0
	s_nop 0
	s_nop 0
	s_nop 0
	s_nop 0
	s_nop 0
	s_nop 0
	s_nop 0
	s_nop 0
	s_nop 0
	s_nop 0
	s_nop 0
	s_nop 0
	s_nop 0
	s_nop 0
	s_nop 0
	s_nop 0
	s_nop 0
	s_nop 0
	s_nop 0
	s_nop 0
	s_nop 0
	s_nop 0
	s_nop 0
	s_nop 0
	s_nop 0
	s_nop 0
	s_nop 0
	s_nop 0
	s_nop 0
	s_nop 0
	s_nop 0
	s_nop 0
	s_nop 0
	s_nop 0
	s_nop 0
	s_nop 0
	s_nop 0
	s_nop 0
	s_nop 0
	s_nop 0
	s_nop 0
	s_nop 0
	s_nop 0
	s_nop 0
	s_nop 0
	s_nop 0
	s_nop 0
	s_nop 0
	s_nop 0
	s_nop 0
	s_nop 0
	s_nop 0
	s_nop 0
	s_nop 0
	s_nop 0
	s_nop 0
	s_nop 0
	s_nop 0
	s_nop 0
	s_nop 0
	s_nop 0
	s_nop 0
	s_nop 0
	s_nop 0
	s_nop 0
	s_nop 0
	s_nop 0
	s_nop 0
	s_nop 0
	s_nop 0
	s_nop 0
	s_nop 0
	s_nop 0
	s_nop 0
	s_nop 0
	s_nop 0
	s_nop 0
	s_nop 0
	s_nop 0
	s_nop 0
	s_nop 0
	s_nop 0
	s_nop 0
	s_nop 0
	s_nop 0
	s_nop 0
	s_nop 0
	s_nop 0
	s_nop 0
	s_nop 0
	s_nop 0
	s_nop 0
	s_nop 0
	s_nop 0
	s_nop 0
	s_nop 0
	s_nop 0
	s_nop 0
	s_nop 0
	s_nop 0
	s_nop 0
	s_nop 0
	s_nop 0
	s_nop 0
	s_nop 0
	s_nop 0
	s_nop 0
	s_nop 0
	s_nop 0
	s_nop 0
	s_nop 0
	s_nop 0
	s_nop 0
	s_nop 0
	s_nop 0
	s_nop 0
	s_nop 0
	s_nop 0
	s_nop 0
	s_nop 0
	s_nop 0
	s_nop 0
	s_nop 0
	s_nop 0
	s_nop 0
	s_nop 0
	s_nop 0
	s_nop 0
	s_nop 0
	s_nop 0
	s_nop 0
	s_nop 0
	s_nop 0
	s_nop 0
	s_nop 0
	s_nop 0
	s_nop 0
	s_nop 0
	s_nop 0
	s_nop 0
	s_nop 0
	s_nop 0
	s_nop 0
	s_nop 0
	s_nop 0
	s_nop 0
	s_nop 0
	s_nop 0
	s_nop 0
	s_nop 0
	s_nop 0
	s_nop 0
	s_nop 0
	s_nop 0
	s_nop 0
	s_nop 0
	s_nop 0
	s_nop 0
	s_nop 0
	s_nop 0
	s_nop 0
	s_nop 0
	s_nop 0
	s_nop 0
	s_nop 0
	s_nop 0
	s_nop 0
	s_nop 0
	s_nop 0
	s_nop 0
	s_nop 0
	s_nop 0
	s_nop 0
	s_nop 0
	s_nop 0
	s_nop 0
	s_nop 0
	s_nop 0
	s_nop 0
	s_nop 0
	s_nop 0
	s_nop 0
	s_nop 0
	s_nop 0
	s_nop 0
	s_nop 0
	s_nop 0
	s_nop 0
	s_nop 0
	s_nop 0
	s_nop 0
	s_nop 0
	s_nop 0
	s_nop 0
	s_nop 0
	s_nop 0
	s_nop 0
	s_nop 0
	s_nop 0
	s_nop 0
	s_nop 0
	s_nop 0
	s_nop 0
	s_nop 0
	s_nop 0
	s_nop 0
	s_nop 0
	s_nop 0
	s_nop 0
	s_nop 0
	s_nop 0
	s_nop 0
	s_nop 0
	s_nop 0
	s_nop 0
	s_nop 0
	s_nop 0
	s_nop 0
	s_nop 0
	s_nop 0
	s_nop 0
	s_nop 0
	s_nop 0
	s_nop 0
	s_nop 0
	s_nop 0
	s_nop 0
	s_nop 0
	s_nop 0
	s_nop 0
	s_nop 0
	s_nop 0
	s_nop 0
	s_nop 0
	s_nop 0
	s_nop 0
	s_nop 0
	s_nop 0
	s_nop 0
	s_nop 0
	s_nop 0
	s_nop 0
	s_nop 0
	s_nop 0
	s_nop 0
	s_nop 0
	s_nop 0
	s_nop 0
	s_nop 0
	s_nop 0
	s_nop 0
	s_nop 0
	s_nop 0
	s_nop 0
	s_nop 0
	s_nop 0
	s_nop 0
	s_nop 0
	s_nop 0
	s_nop 0
	s_nop 0
	s_nop 0
	s_nop 0
	s_nop 0
	s_nop 0
	s_nop 0
	s_nop 0
	s_nop 0
	s_nop 0
	s_nop 0
	s_nop 0
	s_nop 0
	s_nop 0
	s_nop 0
	s_nop 0
	s_nop 0
	s_nop 0
	s_nop 0
	s_nop 0
	s_nop 0
	s_nop 0
	s_nop 0
	s_nop 0
	s_nop 0
	s_nop 0
	s_nop 0
	s_nop 0
	s_nop 0
	s_nop 0
	s_nop 0
	s_nop 0
	s_nop 0
	s_nop 0
	s_nop 0
	s_nop 0
	s_nop 0
	s_nop 0
	s_nop 0
; __device__ __forceinline__ void gla_item(const Params& p, unsigned char* sm, int h, int job0, int jobstride, int nchunks, int tok0, int nvalid, const float* s_init, float* s_out, const int TIDX) {
;     ...
;     }
	s_nop 0
	s_nop 0
	s_nop 0
	s_nop 0
	s_nop 0
	s_nop 0
	s_nop 0
	s_nop 0
	s_nop 0
	s_nop 0
	s_nop 0
	s_nop 0
	s_nop 0
	s_nop 0
	s_nop 0
	s_nop 0
	s_nop 0
	s_nop 0
	s_nop 0
	s_nop 0
	s_nop 0
	s_nop 0
	s_nop 0
	s_nop 0
	s_nop 0
	s_nop 0
	s_nop 0
	s_nop 0
	s_nop 0
	s_nop 0
	s_nop 0
	s_nop 0
	s_nop 0
	s_nop 0
	s_nop 0
	s_nop 0
	s_nop 0
	s_nop 0
	s_nop 0
	s_nop 0
	s_nop 0
	s_nop 0
	s_nop 0
	s_nop 0
	s_nop 0
	s_nop 0
	s_nop 0
	s_nop 0
	s_nop 0
	s_nop 0
	s_nop 0
	s_nop 0
	s_nop 0
	s_nop 0
	s_nop 0
	s_nop 0
	s_nop 0
	s_nop 0
	s_nop 0
	s_nop 0
	s_nop 0
	s_nop 0
	s_nop 0
	s_nop 0
	s_nop 0
	s_nop 0
	s_nop 0
	s_nop 0
	s_nop 0
	s_nop 0
	s_nop 0
	s_nop 0
	s_nop 0
	s_nop 0
	s_nop 0
	s_nop 0
	s_nop 0
	s_nop 0
	s_nop 0
	s_nop 0
	s_nop 0
	s_nop 0
	s_nop 0
	s_nop 0
	s_nop 0
	s_nop 0
	s_nop 0
	s_nop 0
	s_nop 0
	s_nop 0
	s_nop 0
	s_nop 0
	s_nop 0
	s_nop 0
	s_nop 0
	s_nop 0
	s_nop 0
	s_nop 0
	s_nop 0
	s_nop 0
	s_nop 0
	s_nop 0
	s_nop 0
	s_nop 0
	s_nop 0
	s_nop 0
	s_nop 0
	s_nop 0
	s_nop 0
	s_nop 0
	s_nop 0
	s_nop 0
	s_nop 0
	s_nop 0
	s_nop 0
	s_nop 0
	s_nop 0
	s_nop 0
	s_nop 0
	s_nop 0
	s_nop 0
	s_nop 0
	s_nop 0
	s_nop 0
	s_nop 0
	s_nop 0
	s_nop 0
	s_nop 0
	s_nop 0
	s_nop 0
	s_nop 0
	s_nop 0
	s_nop 0
	s_nop 0
	s_nop 0
	s_nop 0
	s_nop 0
	s_nop 0
	s_nop 0
	s_nop 0
	s_nop 0
	s_nop 0
	s_nop 0
	s_nop 0
	s_nop 0
	s_nop 0
	s_nop 0
	s_nop 0
	s_nop 0
	s_nop 0
	s_nop 0
	s_nop 0
	s_nop 0
	s_nop 0
	s_nop 0
	s_nop 0
	s_nop 0
	s_nop 0
	s_nop 0
	s_nop 0
	s_nop 0
	s_nop 0
	s_nop 0
	s_nop 0
	s_nop 0
	s_nop 0
	s_nop 0
	s_nop 0
	s_nop 0
	s_nop 0
	s_nop 0
	s_nop 0
	s_nop 0
	s_nop 0
	s_nop 0
	s_nop 0
	s_nop 0
	s_nop 0
	s_nop 0
	s_nop 0
	s_nop 0
	s_nop 0
	s_nop 0
	s_nop 0
	s_nop 0
	s_nop 0
	s_nop 0
	s_nop 0
	s_nop 0
	s_nop 0
	s_nop 0
	s_nop 0
	s_nop 0
	s_nop 0
	s_nop 0
	s_nop 0
	s_nop 0
	s_nop 0
	s_nop 0
	s_nop 0
	s_nop 0
	s_nop 0
	s_nop 0
	s_nop 0
	s_nop 0
	s_nop 0
	s_nop 0
	s_nop 0
	s_nop 0
	s_nop 0
	s_nop 0
	s_nop 0
	s_nop 0
	s_nop 0
	s_nop 0
	s_nop 0
	s_nop 0
	s_nop 0
	s_nop 0
	s_nop 0
	s_nop 0
	s_nop 0
	s_nop 0
	s_nop 0
	s_nop 0
	s_nop 0
	s_nop 0
	s_nop 0
	s_nop 0
	s_nop 0
	s_nop 0
	s_nop 0
	s_nop 0
	s_nop 0
	s_nop 0
	s_nop 0
	s_nop 0
	s_nop 0
	s_nop 0
	s_nop 0
	s_nop 0
	s_nop 0
	s_nop 0
	s_nop 0
	s_nop 0
	s_nop 0
	s_nop 0
	s_nop 0
	s_nop 0
	s_nop 0
	s_nop 0
	s_nop 0
	s_nop 0
	s_nop 0
	s_nop 0
	s_nop 0
	s_nop 0
	s_nop 0
	s_nop 0
	s_nop 0
	s_nop 0
	s_nop 0
	s_nop 0
	s_nop 0
	s_nop 0
	s_nop 0
	s_nop 0
	s_nop 0
	s_nop 0
	s_nop 0
	s_nop 0
	s_nop 0
	s_nop 0
	s_nop 0
	s_nop 0
	s_nop 0
	s_nop 0
	s_nop 0
	s_nop 0
	s_nop 0
	s_nop 0
	s_nop 0
	s_nop 0
	s_nop 0
	s_nop 0
	s_nop 0
	s_nop 0
	s_nop 0
	s_nop 0
	s_nop 0
	s_nop 0
	s_nop 0
	s_nop 0
	s_nop 0
	s_nop 0
	s_nop 0
	s_nop 0
	s_nop 0
	s_nop 0
	s_nop 0
	s_nop 0
	s_nop 0
	s_nop 0
	s_nop 0
	s_nop 0
	s_nop 0
	s_nop 0
	s_nop 0
	s_nop 0
	s_nop 0
	s_nop 0
	s_nop 0
	s_nop 0
	s_nop 0
	s_nop 0
	s_nop 0
	s_nop 0
	s_nop 0
	s_nop 0
	s_nop 0
	s_nop 0
	s_nop 0
	s_nop 0
	s_nop 0
	s_nop 0
	s_nop 0
	s_nop 0
	s_nop 0
	s_nop 0
	s_nop 0
	s_nop 0
	s_nop 0
	s_nop 0
	s_nop 0
	s_nop 0
	s_nop 0
	s_nop 0
	s_nop 0
	s_nop 0
	s_nop 0
	s_nop 0
	s_nop 0
	s_nop 0
	s_nop 0
	s_nop 0
	s_nop 0
	s_nop 0
	s_nop 0
	s_nop 0
	s_nop 0
	s_nop 0
	s_nop 0
	s_nop 0
	s_nop 0
	s_nop 0
	s_nop 0
	s_nop 0
	s_nop 0
	s_nop 0
	s_nop 0
	s_nop 0
	s_nop 0
	s_nop 0
	s_nop 0
	s_nop 0
	s_nop 0
	s_nop 0
	s_nop 0
	s_nop 0
	s_nop 0
	s_nop 0
	s_nop 0
	s_nop 0
	s_nop 0
	s_nop 0
	s_nop 0
	s_nop 0
	s_nop 0
	s_nop 0
	s_nop 0
	s_nop 0
	s_nop 0
	s_nop 0
	s_nop 0
	s_nop 0
	s_nop 0
	s_nop 0
	s_nop 0
	s_nop 0
	s_nop 0
	s_nop 0
	s_nop 0
	s_nop 0
	s_nop 0
	s_nop 0
	s_nop 0
	s_nop 0
	s_nop 0
	s_nop 0
	s_nop 0
	s_nop 0
	s_nop 0
	s_nop 0
	s_nop 0
	s_nop 0
	s_nop 0
	s_nop 0
	s_nop 0
	s_nop 0
	s_nop 0
	s_nop 0
	s_nop 0
	s_nop 0
	s_nop 0
	s_nop 0
	s_nop 0
	s_nop 0
	s_nop 0
	s_nop 0
	s_nop 0
	s_nop 0
	s_nop 0
	s_nop 0
	s_nop 0
	s_nop 0
	s_nop 0
	s_nop 0
	s_nop 0
	s_nop 0
	s_nop 0
	s_nop 0
	s_nop 0
	s_nop 0
	s_nop 0
	s_nop 0
	s_nop 0
	s_nop 0
	s_nop 0
	s_nop 0
	s_nop 0
	s_nop 0
	s_nop 0
	s_nop 0
	s_nop 0
	s_nop 0
	s_nop 0
	s_nop 0
	s_nop 0
	s_nop 0
	s_nop 0
	s_nop 0
	s_nop 0
	s_nop 0
	s_nop 0
	s_nop 0
	s_nop 0
	s_nop 0
	s_nop 0
	s_nop 0
	s_nop 0
	s_nop 0
	s_nop 0
	s_nop 0
	s_nop 0
	s_nop 0
	s_nop 0
	s_nop 0
	s_nop 0
	s_nop 0
	s_nop 0
	s_nop 0
	s_nop 0
	s_nop 0
	s_nop 0
	s_nop 0
	s_nop 0
	s_nop 0
	s_nop 0
	s_nop 0
	s_nop 0
	s_nop 0
	s_nop 0
	s_nop 0
	s_nop 0
	s_nop 0
	s_nop 0
	s_nop 0
	s_nop 0
	s_nop 0
	s_nop 0
	s_nop 0
	s_nop 0
	s_nop 0
	s_nop 0
	s_nop 0
	s_nop 0
	s_nop 0
	s_nop 0
	s_nop 0
	s_nop 0
	s_nop 0
	s_nop 0
	s_nop 0
	s_nop 0
	s_nop 0
	s_nop 0
	s_nop 0
	s_nop 0
	s_nop 0
